# plus: LRU pass-1 carry-in recurrences merged into one loop
# speedup vs baseline: 1.0108x; 1.0021x over previous
; #define LAS __attribute__((address_space(3)))
; template <int pass>
; __device__ __forceinline__ void lru_item(const Ctx& a, LAS unsigned char* lds, int l, int b, int n, int seg, const int tid) {
;     ...
;         for (int i = 0; i < 2; ++i) { const int v = tid + 512 * i, mat = v >> 9, row = (v >> 3) & 63, c8 = v & 7; *(LAS u32x4*)(WLs + mat * 9216 + row * 144 + c8 * 16) = wpre[i]; }
;         if (pass == 1) *(LAS f32x4*)(AGs + 4 * tid) = agpre;
;         float ba[4], bi[4], sp[4], hin[4], ain[4];
; #pragma unroll
;         for (int nt = 0; nt < 4; ++nt) { hin[nt] = 0.f; ain[nt] = 1.f; }
;         __syncthreads();
; #pragma unroll
;         for (int nt = 0; nt < 4; ++nt) { ba[nt] = CPs[dir * 192 + 16 * nt + c15]; bi[nt] = CPs[dir * 192 + 64 + 16 * nt + c15]; sp[nt] = CPs[dir * 192 + 128 + 16 * nt + c15]; }
;         if (pass == 1) {
; #pragma unroll
;             for (int nt = 0; nt < 4; ++nt) { float h0 = 0.f;
;                 if (dir == 0) { for (int s2 = 0; s2 < seg; ++s2) { const LAS float* q = AGs + s2 * 128 + (16 * nt + c15) * 2; h0 = q[0] * h0 + q[1]; } }
;     ...
;                 hin[nt] = h0; }
.LBB0_379:
	s_or_b64 exec, exec, s[40:41]
	v_bfe_u32 v0, v56, 3, 6
	v_lshlrev_b32_e32 v2, 4, v56
	v_mul_u32_u24_e32 v0, 0x90, v0
	v_and_b32_e32 v3, 0x70, v2
	v_readlane_b32 s6, v245, 22
	v_and_b32_e32 v122, 15, v56
	v_lshl_add_u32 v142, v122, 2, 0
	v_add3_u32 v140, s6, v0, v3
	v_add_u32_e32 v0, 0, v2
	s_movk_i32 s6, 0x2400
	v_add_u32_e32 v141, 0x1e600, v0
	v_mad_i32_i24 v0, v58, s6, v140
	s_waitcnt vmcnt(0)
	ds_write_b128 v0, v[36:39]
	v_mad_i32_i24 v0, v60, s6, v140
	ds_write_b128 v0, v[40:43]
	ds_write_b128 v141, v[44:47]
	v_add_u32_e32 v0, 0x20b00, v142
	s_waitcnt lgkmcnt(0)
	s_barrier
	v_add_u32_e32 v2, 0x20c00, v142
	v_add_u32_e32 v3, 0x20d00, v142
	ds_read2_b32 v[62:63], v0 offset1:16
	ds_read2_b32 v[64:65], v2 offset1:16
	ds_read2_b32 v[66:67], v3 offset1:16
	ds_read2_b32 v[68:69], v0 offset0:32 offset1:48
	ds_read2_b32 v[70:71], v2 offset0:32 offset1:48
	ds_read2_b32 v[72:73], v3 offset0:32 offset1:48
	s_cmp_lt_i32 s88, 15
	s_cselect_b64 s[6:7], -1, 0
	v_lshlrev_b32_e32 v138, 3, v122
	v_cndmask_b32_e64 v0, 0, 1, s[6:7]
	v_mul_i32_i24_e32 v144, 0x2400, v58
	v_mul_i32_i24_e32 v143, 0x2400, v60
	v_cmp_ne_u32_e64 s[40:41], 1, v0
	v_mov_b32_e32 v3, 0
	v_mov_b32_e32 v75, 0
	v_mov_b32_e32 v101, 0
	v_mov_b32_e32 v99, 0
	s_cmp_gt_i32 s88, 14
	s_cbranch_scc1 .Llru_bwc_done
	v_readlane_b32 s10, v245, 23
	s_nop 1
	v_add3_u32 v228, s10, v138, -4
	v_readlane_b32 s10, v245, 24
	s_nop 1
	v_add3_u32 v229, s10, v138, -4
	v_readlane_b32 s10, v245, 25
	s_nop 1
	v_add3_u32 v230, s10, v138, -4
	v_readlane_b32 s10, v245, 26
	s_nop 1
	v_add3_u32 v231, s10, v138, -4
	s_mov_b32 s14, 15
.Llru_bwc_loop:
	ds_read_b64 v[232:233], v228
	ds_read_b64 v[234:235], v229
	ds_read_b64 v[236:237], v230
	ds_read_b64 v[238:239], v231
	s_add_i32 s14, s14, -1
	v_add_u32_e32 v228, 0xfffffe00, v228
	v_add_u32_e32 v229, 0xfffffe00, v229
	v_add_u32_e32 v230, 0xfffffe00, v230
	v_add_u32_e32 v231, 0xfffffe00, v231
	s_cmp_gt_i32 s14, s88
	s_waitcnt lgkmcnt(0)
	v_fma_f32 v3, v3, v232, v233
	v_fma_f32 v75, v75, v234, v235
	v_fma_f32 v101, v101, v236, v237
	v_fma_f32 v99, v99, v238, v239
	s_cbranch_scc1 .Llru_bwc_loop
; #define LAS __attribute__((address_space(3)))
; __device__ __forceinline__ float bflo(unsigned w) { return __uint_as_float(w << 16); }
; template <int pass>
; __device__ __forceinline__ void lru_item(const Ctx& a, LAS unsigned char* lds, int l, int b, int n, int seg, const int tid) {
;     ...
;                 if (dir == 0) { for (int s2 = 0; s2 < seg; ++s2) { const LAS float* q = AGs + s2 * 128 + (16 * nt + c15) * 2; h0 = q[0] * h0 + q[1]; } }
;     ...
;                 hin[nt] = h0; }
;     ...
;         for (int c = 0; c < LSEG / 128; ++c) {
;             const int tl0 = dir ? LSEG - 128 * (c + 1) : 128 * c;
; #pragma unroll
;             for (int rep = 0; rep < 2; ++rep) {
;                 const int tokl = (tid + 512 * rep) >> 3, i = dir ? 127 - tokl : tokl;
;                 f32x4 o0 = *(const LAS f32x4*)(CWs + 256 + 8 * cg8), o1 = *(const LAS f32x4*)(CWs + 256 + 8 * cg8 + 4);
; #pragma unroll
;                 for (int tap = 0; tap < 4; ++tap) {
;                     const u32x4 xv = xr[rep][tap];
;                     const f32x4 w0 = *(const LAS f32x4*)(CWs + tap * 64 + 8 * cg8), w1 = *(const LAS f32x4*)(CWs + tap * 64 + 8 * cg8 + 4);
;                     o0[0] += bflo(xv.x) * w0[0]; o0[1] += bfhi(xv.x) * w0[1]; o0[2] += bflo(xv.y) * w0[2]; o0[3] += bfhi(xv.y) * w0[3];
;                     o1[0] += bflo(xv.z) * w1[0]; o1[1] += bfhi(xv.z) * w1[1]; o1[2] += bflo(xv.w) * w1[2]; o1[3] += bfhi(xv.w) * w1[3];
;                 }
;                 *(LAS f32x4*)(XC + i * 68 + 8 * cg8) = o0;
;                 *(LAS f32x4*)(XC + i * 68 + 8 * cg8 + 4) = o1;
;             }
;             if (c + 1 < LSEG / 128) load_x(dir, c + 1);
;             bf16_t gq[4][4];
;             const unsigned gbase = ((unsigned)((int)tok0 + seg * LSEG + tl0 + 16 * w + 4 * g) * (unsigned)PC + (unsigned)(2048 + cb + c15)) * 2u;
;             if (pass == 1 && sweep == 1) {
; #pragma unroll
;                 for (int nt = 0; nt < 4; ++nt)
; #pragma unroll
;                     for (int jj = 0; jj < 4; ++jj) gq[nt][jj] = *(const bf16_t*)((const char*)PB + gbase + (unsigned)(jj * PC * 2 + nt * 32));
;             }
;             __syncthreads();
;             bf16x8 Af[2];
; #pragma unroll
;             for (int kc = 0; kc < 2; ++kc) { const f32x4 x0 = *(const LAS f32x4*)(XC + (16 * w + c15) * 68 + 32 * kc + 8 * g), x1 = *(const LAS f32x4*)(XC + (16 * w + c15) * 68 + 32 * kc + 8 * g + 4);
.Llru_bwc_done:
.LBB0_391:
	v_ashrrev_i32_e32 v2, 6, v56
	v_lshlrev_b32_e32 v0, 5, v105
	v_lshlrev_b32_e32 v129, 4, v2
	v_add_u32_e32 v139, 0, v0
	v_or_b32_e32 v0, v129, v122
	v_mul_lo_u32 v0, v0, s92
	v_add_u32_e32 v98, 0, v0
	v_add_u32_e32 v0, -16, v169
	v_and_b32_e32 v49, 64, v169
	v_cmp_lt_i32_e32 vcc, v0, v49
	v_lshl_add_u64 v[52:53], s[28:29], 0, v[52:53]
	v_mov_b32_e32 v51, v1
	v_cndmask_b32_e32 v0, v0, v169, vcc
	v_lshlrev_b32_e32 v111, 2, v0
	v_subrev_u32_e32 v0, 32, v169
	v_cmp_lt_i32_e32 vcc, v0, v49
	v_mov_b32_e32 v49, v1
	v_lshl_add_u64 v[52:53], v[52:53], 0, v[48:49]
	s_ashr_i32 s43, s42, 31
	v_lshl_add_u64 v[80:81], v[76:77], 2, s[2:3]
	v_lshl_add_u64 v[76:77], v[52:53], 0, v[50:51]
	v_lshl_add_u64 v[52:53], s[28:29], 0, v[54:55]
	s_lshl_b64 s[2:3], s[42:43], 13
	v_lshl_add_u64 v[48:49], v[52:53], 0, v[48:49]
	v_lshl_add_u64 v[80:81], v[80:81], 0, s[2:3]
	s_add_i32 s2, s22, -2
	v_cndmask_b32_e32 v0, v0, v169, vcc
	v_lshl_add_u64 v[78:79], v[48:49], 0, v[50:51]
	v_add_u32_e32 v50, s2, v103
	v_lshlrev_b32_e32 v112, 2, v0
	v_add_u32_e32 v0, s85, v50
	v_mul_lo_u32 v0, v0, s37
	v_add_u32_e32 v0, s16, v0
	v_lshl_or_b32 v0, v0, 1, v102
	v_add_u32_e32 v48, 1, v50
	v_cmp_gt_u32_e64 s[64:65], s83, v48
	v_add_u32_e32 v48, 0x1800, v0
	v_mov_b32_e32 v49, v1
	v_lshl_add_u64 v[84:85], s[90:91], 0, v[48:49]
	v_add_u32_e32 v48, s22, v103
	v_cmp_gt_u32_e64 s[66:67], s83, v48
	v_add_u32_e32 v48, 0x3000, v0
	v_cmp_gt_u32_e64 s[62:63], s83, v50
	v_lshl_add_u64 v[82:83], s[90:91], 0, v[0:1]
	v_lshl_add_u64 v[86:87], s[90:91], 0, v[48:49]
	v_add_u32_e32 v48, 3, v50
	v_add_u32_e32 v0, 0x4800, v0
	v_add_u32_e32 v50, s2, v137
	v_lshl_add_u64 v[88:89], s[90:91], 0, v[0:1]
	v_add_u32_e32 v0, s85, v50
	v_mul_lo_u32 v0, v0, s37
	v_add_u32_e32 v0, s16, v0
	v_cmp_gt_u32_e64 s[96:97], s83, v48
	v_lshl_or_b32 v0, v0, 1, v102
	v_add_u32_e32 v48, 1, v50
	v_cmp_gt_u32_e64 s[70:71], s83, v48
	v_add_u32_e32 v48, 0x1800, v0
	v_lshl_add_u64 v[92:93], s[90:91], 0, v[48:49]
	v_add_u32_e32 v48, s22, v137
	s_cmpk_gt_u32 s2, 0x1f7c
	v_cmp_gt_u32_e64 s[72:73], s83, v48
	v_add_u32_e32 v48, 0x3000, v0
	v_readlane_b32 s3, v245, 22
	s_movk_i32 s2, 0x90
	v_readlane_b32 s7, v245, 27
	s_cselect_b64 s[92:93], -1, 0
	v_cmp_gt_u32_e64 s[68:69], s83, v50
	v_lshl_add_u64 v[94:95], s[90:91], 0, v[48:49]
	v_add_u32_e32 v48, 3, v50
	v_mov_b32_e32 v49, s3
	v_mov_b32_e32 v50, s7
	v_mad_u32_u24 v52, v122, s2, v174
	v_mad_u32_u24 v54, v122, s2, v175
	v_mad_u32_u24 v57, v122, s2, v176
	s_lshl_b32 s34, s86, 9
	v_mad_u32_u24 v49, v122, s2, v49
	v_mad_u32_u24 v50, v122, s2, v50
	v_add_u32_e32 v53, s3, v52
	v_add_u32_e32 v55, s3, v54
	v_add_u32_e32 v119, s3, v57
	v_add_u32_e32 v120, s34, v137
	s_lshl_b32 s35, s84, 13
	s_mul_i32 s2, s87, 0x3000000
	s_mul_i32 s3, s86, 0x300000
	v_subrev_u32_e32 v131, s35, v120
	s_add_i32 s2, s2, s3
	v_mul_lo_u32 v120, v137, s23
	v_add_u32_e32 v147, s2, v120
	s_lshl_b32 s82, s20, 7
	v_or_b32_e32 v120, s82, v147
	v_subrev_u32_e32 v153, s89, v120
	v_add_u32_e32 v120, s34, v103
	v_subrev_u32_e32 v132, s35, v120
	v_mul_lo_u32 v120, v103, s23
	v_add_u32_e32 v110, 0, v138
	v_add_u32_e32 v150, s2, v120
	v_bfe_u32 v74, v56, 4, 2
	v_mad_i32_i24 v114, v122, -6, v110
	v_or_b32_e32 v120, s82, v150
	v_mad_u32_u24 v100, v122, 6, v114
	v_subrev_u32_e32 v154, s89, v120
	v_mad_i32_i24 v120, v122, -6, v138
	v_lshlrev_b32_e32 v151, 9, v74
	v_lshlrev_b32_e32 v130, 2, v74
	v_lshlrev_b32_e32 v117, 5, v74
	v_lshlrev_b32_e32 v118, 4, v74
	v_cmp_eq_u32_e64 s[56:57], 0, v74
	v_cmp_lt_u32_e64 s[60:61], 1, v74
	v_cmp_eq_u32_e64 s[58:59], 3, v74
	v_lshl_add_u64 v[90:91], s[90:91], 0, v[0:1]
	v_add_u32_e32 v0, 0x4800, v0
	v_mad_i32_i24 v115, v122, -6, v100
	v_sub_u32_e32 v74, v120, v151
	v_lshlrev_b32_e32 v152, 11, v2
	v_or_b32_e32 v109, v130, v129
	s_movk_i32 s6, 0x110
	v_cmp_gt_u32_e64 s[28:29], s83, v48
	v_lshl_add_u64 v[96:97], s[90:91], 0, v[0:1]
	v_sub_u32_e32 v0, 0x7f, v103
	v_sub_u32_e32 v48, 0x7f, v137
	v_cmp_eq_u32_e64 s[52:53], 1, v2
	v_cmp_eq_u32_e64 s[50:51], 2, v2
	v_cmp_eq_u32_e64 s[48:49], 3, v2
	v_cmp_eq_u32_e64 s[46:47], 4, v2
	v_cmp_eq_u32_e64 s[44:45], 5, v2
	v_cmp_eq_u32_e64 s[42:43], 6, v2
	v_cmp_eq_u32_e64 s[40:41], 7, v2
	v_mad_u32_u24 v61, v122, 6, v115
	v_sub_u32_e32 v2, v74, v152
	v_readlane_b32 s2, v245, 28
	v_mul_lo_u32 v0, v0, s6
	v_mul_lo_u32 v48, v48, s6
	v_mul_lo_u32 v51, v109, s6
	v_add_u32_e32 v52, s7, v52
	v_add_u32_e32 v54, s7, v54
	v_add_u32_e32 v133, s7, v57
	v_mul_i32_i24_e32 v113, -6, v122
	v_mul_u32_u24_e32 v145, 6, v122
	v_mad_i32_i24 v116, v122, -6, v61
	v_add_u32_e32 v155, s2, v2
	s_movk_i32 s2, 0x1a0
	s_mov_b32 s36, 0
	v_and_b32_e32 v123, 0xfffffe78, v104
	v_cmp_gt_u32_e64 s[54:55], 64, v56
	v_mad_u32_u24 v57, v122, 6, v116
	v_add3_u32 v156, v145, v113, s2
	v_add_u32_e32 v157, v139, v0
	v_add_u32_e32 v158, v139, v48
	v_add_u32_e32 v128, v98, v117
	v_add_u32_e32 v127, v49, v118
	v_add_u32_e32 v126, v50, v118
	v_add_u32_e32 v117, v142, v51
	v_add_u32_e32 v125, v53, v118
	v_add_u32_e32 v124, v52, v118
	v_add_u32_e32 v121, v55, v118
	v_add_u32_e32 v120, v54, v118
	v_add_u32_e32 v119, v119, v118
	v_add_u32_e32 v118, v133, v118
	v_mov_b32_e32 v74, v3
	v_mov_b32_e32 v98, v101
	s_branch .LBB0_394

; #define LAS __attribute__((address_space(3)))
; __device__ __forceinline__ float bflo(unsigned w) { return __uint_as_float(w << 16); }
; __device__ __forceinline__ float bfhi(unsigned w) { return __uint_as_float(w & 0xffff0000u); }
; template <int pass>
; __device__ __forceinline__ void lru_item(const Ctx& a, LAS unsigned char* lds, int l, int b, int n, int seg, const int tid) {
;     ...
;         for (int nt = 0; nt < 4; ++nt) { ba[nt] = CPs[dir * 192 + 16 * nt + c15]; bi[nt] = CPs[dir * 192 + 64 + 16 * nt + c15]; sp[nt] = CPs[dir * 192 + 128 + 16 * nt + c15]; }
;         if (pass == 1) {
; #pragma unroll
;             for (int nt = 0; nt < 4; ++nt) { float h0 = 0.f;
;                 if (dir == 0) { for (int s2 = 0; s2 < seg; ++s2) { const LAS float* q = AGs + s2 * 128 + (16 * nt + c15) * 2; h0 = q[0] * h0 + q[1]; } }
;     ...
;                 hin[nt] = h0; }
;     ...
;         for (int c = 0; c < LSEG / 128; ++c) {
;             const int tl0 = dir ? LSEG - 128 * (c + 1) : 128 * c;
; #pragma unroll
;             for (int rep = 0; rep < 2; ++rep) {
;                 const int tokl = (tid + 512 * rep) >> 3, i = dir ? 127 - tokl : tokl;
;                 f32x4 o0 = *(const LAS f32x4*)(CWs + 256 + 8 * cg8), o1 = *(const LAS f32x4*)(CWs + 256 + 8 * cg8 + 4);
; #pragma unroll
;                 for (int tap = 0; tap < 4; ++tap) {
;                     const u32x4 xv = xr[rep][tap];
;                     const f32x4 w0 = *(const LAS f32x4*)(CWs + tap * 64 + 8 * cg8), w1 = *(const LAS f32x4*)(CWs + tap * 64 + 8 * cg8 + 4);
;                     o0[0] += bflo(xv.x) * w0[0]; o0[1] += bfhi(xv.x) * w0[1]; o0[2] += bflo(xv.y) * w0[2]; o0[3] += bfhi(xv.y) * w0[3];
;                     o1[0] += bflo(xv.z) * w1[0]; o1[1] += bfhi(xv.z) * w1[1]; o1[2] += bflo(xv.w) * w1[2]; o1[3] += bfhi(xv.w) * w1[3];
;                 }
;                 *(LAS f32x4*)(XC + i * 68 + 8 * cg8) = o0;
;                 *(LAS f32x4*)(XC + i * 68 + 8 * cg8 + 4) = o1;
;             }
;             if (c + 1 < LSEG / 128) load_x(dir, c + 1);
;             bf16_t gq[4][4];
;             const unsigned gbase = ((unsigned)((int)tok0 + seg * LSEG + tl0 + 16 * w + 4 * g) * (unsigned)PC + (unsigned)(2048 + cb + c15)) * 2u;
.LBB0_453:
	v_add_u32_e32 v0, v140, v144
	s_waitcnt lgkmcnt(0)
	s_barrier
	s_waitcnt vmcnt(2)
	ds_write_b128 v0, v[36:39]
	v_add_u32_e32 v0, v140, v143
	s_waitcnt vmcnt(1)
	ds_write_b128 v0, v[40:43]
	s_waitcnt vmcnt(0)
	ds_write_b128 v141, v[44:47]
	v_add_u32_e32 v0, 0x20800, v142
	s_waitcnt lgkmcnt(0)
	s_barrier
	v_add_u32_e32 v2, 0x20900, v142
	v_add_u32_e32 v3, 0x20a00, v142
	ds_read2_b32 v[64:65], v0 offset1:16
	ds_read2_b32 v[62:63], v2 offset1:16
	ds_read2_b32 v[54:55], v3 offset1:16
	ds_read2_b32 v[52:53], v0 offset0:32 offset1:48
	ds_read2_b32 v[50:51], v2 offset0:32 offset1:48
	ds_read2_b32 v[48:49], v3 offset0:32 offset1:48
	s_cmp_gt_i32 s88, 0
	s_cselect_b64 s[2:3], -1, 0
	v_cndmask_b32_e64 v0, 0, 1, s[2:3]
	v_cmp_ne_u32_e64 s[62:63], 1, v0
	v_mov_b32_e32 v46, 0
	v_mov_b32_e32 v47, 0
	v_mov_b32_e32 v44, 0
	v_mov_b32_e32 v45, 0
	s_movk_i32 s10, 0x4000
	s_movk_i32 s93, 0x1000
	s_movk_i32 s37, 0xc00
	s_movk_i32 s92, 0x110
	s_mov_b32 s65, 0x13fff
	s_mov_b32 s97, 0x800000
	s_mov_b64 s[16:17], 0x1800
	s_mov_b64 s[18:19], 0x3000
	s_mov_b64 s[66:67], 0x4800
	s_mov_b64 s[68:69], 0x1820
	s_mov_b64 s[70:71], 0x3020
	s_mov_b64 s[4:5], 0x4820
	s_cmp_lt_i32 s88, 1
	s_cbranch_scc1 .Llru_fwc_done
	v_readlane_b32 s6, v245, 29
	s_nop 1
	v_add3_u32 v228, s6, v138, -4
	v_readlane_b32 s6, v245, 30
	s_nop 1
	v_add3_u32 v229, s6, v138, -4
	v_readlane_b32 s6, v245, 31
	s_nop 1
	v_add3_u32 v230, s6, v138, -4
	v_readlane_b32 s6, v245, 32
	s_nop 1
	v_add3_u32 v231, s6, v138, -4
	s_mov_b32 s6, s88
.Llru_fwc_loop:
	ds_read_b64 v[232:233], v228
	ds_read_b64 v[234:235], v229
	ds_read_b64 v[236:237], v230
	ds_read_b64 v[238:239], v231
	s_add_i32 s6, s6, -1
	v_add_u32_e32 v228, 0x200, v228
	v_add_u32_e32 v229, 0x200, v229
	v_add_u32_e32 v230, 0x200, v230
	v_add_u32_e32 v231, 0x200, v231
	s_cmp_lg_u32 s6, 0
	s_waitcnt lgkmcnt(0)
	v_fma_f32 v46, v46, v232, v233
	v_fma_f32 v47, v47, v234, v235
	v_fma_f32 v44, v44, v236, v237
	v_fma_f32 v45, v45, v238, v239
	s_cbranch_scc1 .Llru_fwc_loop
.Llru_fwc_done:
.LBB0_469:
	v_add_u32_e32 v3, v147, v102
	v_subrev_u32_e32 v88, s89, v3
	v_add_u32_e32 v3, v150, v102
	v_subrev_u32_e32 v89, s89, v3
	v_add3_u32 v3, v113, v152, v151
	v_readlane_b32 s2, v245, 33
	v_mul_lo_u32 v0, v103, s92
	v_mul_lo_u32 v2, v137, s92
	v_add3_u32 v90, v3, v138, s2
	s_add_i32 s2, s85, s34
	v_add3_u32 v3, s2, v129, v130
	v_subrev_u32_e32 v3, s35, v3
	v_mul_lo_u32 v3, v3, s23
	v_lshl_or_b32 v91, v122, 1, v3
	v_add3_u32 v92, v145, v113, 32
	s_mov_b32 s28, 0
	v_add_u32_e32 v87, v139, v0
	v_add_u32_e32 v86, v139, v2
	s_branch .LBB0_471
